# RESID epilogue rewritten by hand: residual loads run 3 groups ahead of the stores with counted vmcnt, gamma/beta loaded once per tile
# speedup vs baseline: 1.0097x; 1.0054x over previous
; #define EPI_END } asm volatile("" ::: "memory"); }
;     __device__ __forceinline__ void operator()(const f32x4 (&acc)[2][2][4][2], const pg8::Unit& u, int wr, int wc, int fr, int fq) const {
;     ...
;         if (mode == EM_RESID) {
;             EPI_BEGIN { const size_t off = (size_t)row * ldc + col; f32x4 r0 = *(const f32x4*)(res + off), r1 = *(const f32x4*)(res + off + 4);
;                 if (p0) { const f32x2 ms = *(const f32x2*)(f0 + 2 * (size_t)row); const f32x4 g0 = *(const f32x4*)(p0 + col), g1 = *(const f32x4*)(p0 + col + 4), b0 = *(const f32x4*)(p1 + col), b1 = *(const f32x4*)(p1 + col + 4);
;                     r0 = (r0 - ms[0]) * ms[1] * g0 + b0; r1 = (r1 - ms[0]) * ms[1] * g1 + b1; }
;                 if (bias) { v0 += *(const f32x4*)(bias + col); v1 += *(const f32x4*)(bias + col + 4); }
;                 *(f32x4*)(outf + off) = r0 * ALPHA + v0; *(f32x4*)(outf + off + 4) = r1 * ALPHA + v1; } EPI_END
.LBB0_1171:
	s_andn2_b64 vcc, exec, s[18:19]
	s_cbranch_vccnz .LBB0_1237
	v_mul_lo_u32 v128, v158, s58
	v_lshlrev_b32_e32 v129, 3, v158
	v_lshlrev_b32_e32 v130, 2, v156
	v_add_lshl_u32 v128, v128, v156, 2
	v_readlane_b32 s18, v255, 34
	v_readlane_b32 s19, v255, 35
	s_mov_b64 s[34:35], s[62:63]
	s_mov_b64 s[44:45], s[60:61]
	s_lshl_b32 s20, s58, 6
	s_mul_i32 s23, s58, 0x140
	s_cmp_lg_u64 s[18:19], 0
	s_cbranch_scc0 .Lmy_res_nobias
	s_nop 4
	global_load_dwordx4 v[132:135], v130, s[18:19]
	global_load_dwordx4 v[156:159], v130, s[18:19] offset:16
	global_load_dwordx4 v[176:179], v130, s[18:19] offset:512
	global_load_dwordx4 v[206:209], v130, s[18:19] offset:528
	s_waitcnt vmcnt(0)
	v_pk_add_f32 v[124:125], v[124:125], v[132:133]
	v_pk_add_f32 v[126:127], v[126:127], v[134:135]
	v_pk_add_f32 v[120:121], v[120:121], v[156:157]
	v_pk_add_f32 v[122:123], v[122:123], v[158:159]
	v_pk_add_f32 v[116:117], v[116:117], v[176:177]
	v_pk_add_f32 v[118:119], v[118:119], v[178:179]
	v_pk_add_f32 v[112:113], v[112:113], v[206:207]
	v_pk_add_f32 v[114:115], v[114:115], v[208:209]
	v_pk_add_f32 v[108:109], v[108:109], v[132:133]
	v_pk_add_f32 v[110:111], v[110:111], v[134:135]
	v_pk_add_f32 v[104:105], v[104:105], v[156:157]
	v_pk_add_f32 v[106:107], v[106:107], v[158:159]
	v_pk_add_f32 v[100:101], v[100:101], v[176:177]
	v_pk_add_f32 v[102:103], v[102:103], v[178:179]
	v_pk_add_f32 v[96:97], v[96:97], v[206:207]
	v_pk_add_f32 v[98:99], v[98:99], v[208:209]
	v_pk_add_f32 v[92:93], v[92:93], v[132:133]
	v_pk_add_f32 v[94:95], v[94:95], v[134:135]
	v_pk_add_f32 v[88:89], v[88:89], v[156:157]
	v_pk_add_f32 v[90:91], v[90:91], v[158:159]
	v_pk_add_f32 v[84:85], v[84:85], v[176:177]
	v_pk_add_f32 v[86:87], v[86:87], v[178:179]
	v_pk_add_f32 v[80:81], v[80:81], v[206:207]
	v_pk_add_f32 v[82:83], v[82:83], v[208:209]
	v_pk_add_f32 v[76:77], v[76:77], v[132:133]
	v_pk_add_f32 v[78:79], v[78:79], v[134:135]
	v_pk_add_f32 v[72:73], v[72:73], v[156:157]
	v_pk_add_f32 v[74:75], v[74:75], v[158:159]
	v_pk_add_f32 v[68:69], v[68:69], v[176:177]
	v_pk_add_f32 v[70:71], v[70:71], v[178:179]
	v_pk_add_f32 v[64:65], v[64:65], v[206:207]
	v_pk_add_f32 v[66:67], v[66:67], v[208:209]
	v_pk_add_f32 v[60:61], v[60:61], v[132:133]
	v_pk_add_f32 v[62:63], v[62:63], v[134:135]
	v_pk_add_f32 v[56:57], v[56:57], v[156:157]
	v_pk_add_f32 v[58:59], v[58:59], v[158:159]
	v_pk_add_f32 v[52:53], v[52:53], v[176:177]
	v_pk_add_f32 v[54:55], v[54:55], v[178:179]
	v_pk_add_f32 v[48:49], v[48:49], v[206:207]
	v_pk_add_f32 v[50:51], v[50:51], v[208:209]
	v_pk_add_f32 v[44:45], v[44:45], v[132:133]
	v_pk_add_f32 v[46:47], v[46:47], v[134:135]
	v_pk_add_f32 v[40:41], v[40:41], v[156:157]
	v_pk_add_f32 v[42:43], v[42:43], v[158:159]
	v_pk_add_f32 v[36:37], v[36:37], v[176:177]
	v_pk_add_f32 v[38:39], v[38:39], v[178:179]
	v_pk_add_f32 v[32:33], v[32:33], v[206:207]
	v_pk_add_f32 v[34:35], v[34:35], v[208:209]
	v_pk_add_f32 v[28:29], v[28:29], v[132:133]
	v_pk_add_f32 v[30:31], v[30:31], v[134:135]
	v_pk_add_f32 v[24:25], v[24:25], v[156:157]
	v_pk_add_f32 v[26:27], v[26:27], v[158:159]
	v_pk_add_f32 v[20:21], v[20:21], v[176:177]
	v_pk_add_f32 v[22:23], v[22:23], v[178:179]
	v_pk_add_f32 v[16:17], v[16:17], v[206:207]
	v_pk_add_f32 v[18:19], v[18:19], v[208:209]
	v_pk_add_f32 v[12:13], v[12:13], v[132:133]
	v_pk_add_f32 v[14:15], v[14:15], v[134:135]
	v_pk_add_f32 v[8:9], v[8:9], v[156:157]
	v_pk_add_f32 v[10:11], v[10:11], v[158:159]
	v_pk_add_f32 v[4:5], v[4:5], v[176:177]
	v_pk_add_f32 v[6:7], v[6:7], v[178:179]
	v_pk_add_f32 v[0:1], v[0:1], v[206:207]
	v_pk_add_f32 v[2:3], v[2:3], v[208:209]
.Lmy_res_nobias:
	s_cmp_lg_u64 s[66:67], 0
	s_cbranch_scc0 .Lmy_res_noln
	global_load_dwordx4 v[190:193], v130, s[66:67]
	global_load_dwordx4 v[224:227], v130, s[78:79]
	global_load_dwordx4 v[194:197], v130, s[66:67] offset:16
	global_load_dwordx4 v[228:231], v130, s[78:79] offset:16
	global_load_dwordx4 v[198:201], v130, s[66:67] offset:512
	global_load_dwordx4 v[232:235], v130, s[78:79] offset:512
	global_load_dwordx4 v[202:205], v130, s[66:67] offset:528
	global_load_dwordx4 v[236:239], v130, s[78:79] offset:528
	global_load_dwordx4 v[132:135], v128, s[34:35]
	global_load_dwordx4 v[156:159], v128, s[34:35] offset:16
	global_load_dwordx2 v[136:137], v129, s[50:51]
	global_load_dwordx4 v[176:179], v128, s[34:35] offset:512
	global_load_dwordx4 v[206:209], v128, s[34:35] offset:528
	s_add_u32 s34, s34, s20
	s_addc_u32 s35, s35, 0
	global_load_dwordx4 v[240:243], v128, s[34:35]
	global_load_dwordx4 v[160:163], v128, s[34:35] offset:16
	global_load_dwordx2 v[210:211], v129, s[50:51] offset:128
	s_waitcnt vmcnt(5)
	v_sub_f32_e32 v132, v132, v136
	v_sub_f32_e32 v133, v133, v136
	v_sub_f32_e32 v134, v134, v136
	v_sub_f32_e32 v135, v135, v136
	v_sub_f32_e32 v156, v156, v136
	v_sub_f32_e32 v157, v157, v136
	v_sub_f32_e32 v158, v158, v136
	v_sub_f32_e32 v159, v159, v136
	v_pk_mul_f32 v[132:133], v[136:137], v[132:133] op_sel:[1,0]
	v_pk_mul_f32 v[134:135], v[136:137], v[134:135] op_sel:[1,0]
	v_pk_mul_f32 v[156:157], v[136:137], v[156:157] op_sel:[1,0]
	v_pk_mul_f32 v[158:159], v[136:137], v[158:159] op_sel:[1,0]
	v_pk_fma_f32 v[132:133], v[190:191], v[132:133], v[224:225]
	v_pk_fma_f32 v[134:135], v[192:193], v[134:135], v[226:227]
	v_pk_fma_f32 v[156:157], v[194:195], v[156:157], v[228:229]
	v_pk_fma_f32 v[158:159], v[196:197], v[158:159], v[230:231]
	v_pk_fma_f32 v[124:125], v[132:133], s[0:1], v[124:125] op_sel_hi:[1,0,1]
	v_pk_fma_f32 v[126:127], v[134:135], s[0:1], v[126:127] op_sel_hi:[1,0,1]
	v_pk_fma_f32 v[120:121], v[156:157], s[0:1], v[120:121] op_sel_hi:[1,0,1]
	v_pk_fma_f32 v[122:123], v[158:159], s[0:1], v[122:123] op_sel_hi:[1,0,1]
	global_store_dwordx4 v128, v[124:127], s[44:45]
	global_store_dwordx4 v128, v[120:123], s[44:45] offset:16
	global_load_dwordx4 v[124:127], v128, s[34:35] offset:512
	global_load_dwordx4 v[120:123], v128, s[34:35] offset:528
	s_waitcnt vmcnt(7)
; #define EPI_END } asm volatile("" ::: "memory"); }
;     __device__ __forceinline__ void operator()(const f32x4 (&acc)[2][2][4][2], const pg8::Unit& u, int wr, int wc, int fr, int fq) const {
;     ...
;             EPI_BEGIN { const size_t off = (size_t)row * ldc + col; f32x4 r0 = *(const f32x4*)(res + off), r1 = *(const f32x4*)(res + off + 4);
;                 if (p0) { const f32x2 ms = *(const f32x2*)(f0 + 2 * (size_t)row); const f32x4 g0 = *(const f32x4*)(p0 + col), g1 = *(const f32x4*)(p0 + col + 4), b0 = *(const f32x4*)(p1 + col), b1 = *(const f32x4*)(p1 + col + 4);
;                     r0 = (r0 - ms[0]) * ms[1] * g0 + b0; r1 = (r1 - ms[0]) * ms[1] * g1 + b1; }
;                 if (bias) { v0 += *(const f32x4*)(bias + col); v1 += *(const f32x4*)(bias + col + 4); }
;                 *(f32x4*)(outf + off) = r0 * ALPHA + v0; *(f32x4*)(outf + off + 4) = r1 * ALPHA + v1; } EPI_END
	v_sub_f32_e32 v176, v176, v136
	v_sub_f32_e32 v177, v177, v136
	v_sub_f32_e32 v178, v178, v136
	v_sub_f32_e32 v179, v179, v136
	v_sub_f32_e32 v206, v206, v136
	v_sub_f32_e32 v207, v207, v136
	v_sub_f32_e32 v208, v208, v136
	v_sub_f32_e32 v209, v209, v136
	v_pk_mul_f32 v[176:177], v[136:137], v[176:177] op_sel:[1,0]
	v_pk_mul_f32 v[178:179], v[136:137], v[178:179] op_sel:[1,0]
	v_pk_mul_f32 v[206:207], v[136:137], v[206:207] op_sel:[1,0]
	v_pk_mul_f32 v[208:209], v[136:137], v[208:209] op_sel:[1,0]
	v_pk_fma_f32 v[176:177], v[198:199], v[176:177], v[232:233]
	v_pk_fma_f32 v[178:179], v[200:201], v[178:179], v[234:235]
	v_pk_fma_f32 v[206:207], v[202:203], v[206:207], v[236:237]
	v_pk_fma_f32 v[208:209], v[204:205], v[208:209], v[238:239]
	v_pk_fma_f32 v[116:117], v[176:177], s[0:1], v[116:117] op_sel_hi:[1,0,1]
	v_pk_fma_f32 v[118:119], v[178:179], s[0:1], v[118:119] op_sel_hi:[1,0,1]
	v_pk_fma_f32 v[112:113], v[206:207], s[0:1], v[112:113] op_sel_hi:[1,0,1]
	v_pk_fma_f32 v[114:115], v[208:209], s[0:1], v[114:115] op_sel_hi:[1,0,1]
	global_store_dwordx4 v128, v[116:119], s[44:45] offset:512
	global_store_dwordx4 v128, v[112:115], s[44:45] offset:528
	s_add_u32 s34, s34, s20
	s_addc_u32 s35, s35, 0
	global_load_dwordx4 v[116:119], v128, s[34:35]
	global_load_dwordx4 v[112:115], v128, s[34:35] offset:16
	global_load_dwordx2 v[244:245], v129, s[50:51] offset:256
	s_waitcnt vmcnt(9)
	v_sub_f32_e32 v240, v240, v210
	v_sub_f32_e32 v241, v241, v210
	v_sub_f32_e32 v242, v242, v210
	v_sub_f32_e32 v243, v243, v210
	v_sub_f32_e32 v160, v160, v210
	v_sub_f32_e32 v161, v161, v210
	v_sub_f32_e32 v162, v162, v210
	v_sub_f32_e32 v163, v163, v210
	v_pk_mul_f32 v[240:241], v[210:211], v[240:241] op_sel:[1,0]
	v_pk_mul_f32 v[242:243], v[210:211], v[242:243] op_sel:[1,0]
	v_pk_mul_f32 v[160:161], v[210:211], v[160:161] op_sel:[1,0]
	v_pk_mul_f32 v[162:163], v[210:211], v[162:163] op_sel:[1,0]
	v_pk_fma_f32 v[240:241], v[190:191], v[240:241], v[224:225]
	v_pk_fma_f32 v[242:243], v[192:193], v[242:243], v[226:227]
	v_pk_fma_f32 v[160:161], v[194:195], v[160:161], v[228:229]
	v_pk_fma_f32 v[162:163], v[196:197], v[162:163], v[230:231]
	v_pk_fma_f32 v[108:109], v[240:241], s[0:1], v[108:109] op_sel_hi:[1,0,1]
	v_pk_fma_f32 v[110:111], v[242:243], s[0:1], v[110:111] op_sel_hi:[1,0,1]
	v_pk_fma_f32 v[104:105], v[160:161], s[0:1], v[104:105] op_sel_hi:[1,0,1]
	v_pk_fma_f32 v[106:107], v[162:163], s[0:1], v[106:107] op_sel_hi:[1,0,1]
	s_add_u32 s44, s44, s20
	s_addc_u32 s45, s45, 0
	global_store_dwordx4 v128, v[108:111], s[44:45]
	global_store_dwordx4 v128, v[104:107], s[44:45] offset:16
	global_load_dwordx4 v[108:111], v128, s[34:35] offset:512
	global_load_dwordx4 v[104:107], v128, s[34:35] offset:528
	s_waitcnt vmcnt(9)
	v_sub_f32_e32 v124, v124, v210
	v_sub_f32_e32 v125, v125, v210
	v_sub_f32_e32 v126, v126, v210
	v_sub_f32_e32 v127, v127, v210
	v_sub_f32_e32 v120, v120, v210
	v_sub_f32_e32 v121, v121, v210
	v_sub_f32_e32 v122, v122, v210
	v_sub_f32_e32 v123, v123, v210
	v_pk_mul_f32 v[124:125], v[210:211], v[124:125] op_sel:[1,0]
	v_pk_mul_f32 v[126:127], v[210:211], v[126:127] op_sel:[1,0]
	v_pk_mul_f32 v[120:121], v[210:211], v[120:121] op_sel:[1,0]
	v_pk_mul_f32 v[122:123], v[210:211], v[122:123] op_sel:[1,0]
	v_pk_fma_f32 v[124:125], v[198:199], v[124:125], v[232:233]
	v_pk_fma_f32 v[126:127], v[200:201], v[126:127], v[234:235]
	v_pk_fma_f32 v[120:121], v[202:203], v[120:121], v[236:237]
	v_pk_fma_f32 v[122:123], v[204:205], v[122:123], v[238:239]
	v_pk_fma_f32 v[100:101], v[124:125], s[0:1], v[100:101] op_sel_hi:[1,0,1]
	v_pk_fma_f32 v[102:103], v[126:127], s[0:1], v[102:103] op_sel_hi:[1,0,1]
	v_pk_fma_f32 v[96:97], v[120:121], s[0:1], v[96:97] op_sel_hi:[1,0,1]
	v_pk_fma_f32 v[98:99], v[122:123], s[0:1], v[98:99] op_sel_hi:[1,0,1]
	global_store_dwordx4 v128, v[100:103], s[44:45] offset:512
	global_store_dwordx4 v128, v[96:99], s[44:45] offset:528
	s_add_u32 s34, s34, s20
	s_addc_u32 s35, s35, 0
	global_load_dwordx4 v[100:103], v128, s[34:35]
	global_load_dwordx4 v[96:99], v128, s[34:35] offset:16
	global_load_dwordx2 v[136:137], v129, s[50:51] offset:384
	s_waitcnt vmcnt(9)
	v_sub_f32_e32 v116, v116, v244
	v_sub_f32_e32 v117, v117, v244
	v_sub_f32_e32 v118, v118, v244
	v_sub_f32_e32 v119, v119, v244
	v_sub_f32_e32 v112, v112, v244
	v_sub_f32_e32 v113, v113, v244
	v_sub_f32_e32 v114, v114, v244
	v_sub_f32_e32 v115, v115, v244
	v_pk_mul_f32 v[116:117], v[244:245], v[116:117] op_sel:[1,0]
	v_pk_mul_f32 v[118:119], v[244:245], v[118:119] op_sel:[1,0]
	v_pk_mul_f32 v[112:113], v[244:245], v[112:113] op_sel:[1,0]
	v_pk_mul_f32 v[114:115], v[244:245], v[114:115] op_sel:[1,0]
	v_pk_fma_f32 v[116:117], v[190:191], v[116:117], v[224:225]
	v_pk_fma_f32 v[118:119], v[192:193], v[118:119], v[226:227]
	v_pk_fma_f32 v[112:113], v[194:195], v[112:113], v[228:229]
	v_pk_fma_f32 v[114:115], v[196:197], v[114:115], v[230:231]
	v_pk_fma_f32 v[92:93], v[116:117], s[0:1], v[92:93] op_sel_hi:[1,0,1]
	v_pk_fma_f32 v[94:95], v[118:119], s[0:1], v[94:95] op_sel_hi:[1,0,1]
	v_pk_fma_f32 v[88:89], v[112:113], s[0:1], v[88:89] op_sel_hi:[1,0,1]
	v_pk_fma_f32 v[90:91], v[114:115], s[0:1], v[90:91] op_sel_hi:[1,0,1]
	s_add_u32 s44, s44, s20
	s_addc_u32 s45, s45, 0
	global_store_dwordx4 v128, v[92:95], s[44:45]
	global_store_dwordx4 v128, v[88:91], s[44:45] offset:16
	global_load_dwordx4 v[92:95], v128, s[34:35] offset:512
	global_load_dwordx4 v[88:91], v128, s[34:35] offset:528
	s_waitcnt vmcnt(9)
; #define EPI_END } asm volatile("" ::: "memory"); }
;     __device__ __forceinline__ void operator()(const f32x4 (&acc)[2][2][4][2], const pg8::Unit& u, int wr, int wc, int fr, int fq) const {
;     ...
;             EPI_BEGIN { const size_t off = (size_t)row * ldc + col; f32x4 r0 = *(const f32x4*)(res + off), r1 = *(const f32x4*)(res + off + 4);
;                 if (p0) { const f32x2 ms = *(const f32x2*)(f0 + 2 * (size_t)row); const f32x4 g0 = *(const f32x4*)(p0 + col), g1 = *(const f32x4*)(p0 + col + 4), b0 = *(const f32x4*)(p1 + col), b1 = *(const f32x4*)(p1 + col + 4);
;                     r0 = (r0 - ms[0]) * ms[1] * g0 + b0; r1 = (r1 - ms[0]) * ms[1] * g1 + b1; }
;                 if (bias) { v0 += *(const f32x4*)(bias + col); v1 += *(const f32x4*)(bias + col + 4); }
;                 *(f32x4*)(outf + off) = r0 * ALPHA + v0; *(f32x4*)(outf + off + 4) = r1 * ALPHA + v1; } EPI_END
	v_sub_f32_e32 v108, v108, v244
	v_sub_f32_e32 v109, v109, v244
	v_sub_f32_e32 v110, v110, v244
	v_sub_f32_e32 v111, v111, v244
	v_sub_f32_e32 v104, v104, v244
	v_sub_f32_e32 v105, v105, v244
	v_sub_f32_e32 v106, v106, v244
	v_sub_f32_e32 v107, v107, v244
	v_pk_mul_f32 v[108:109], v[244:245], v[108:109] op_sel:[1,0]
	v_pk_mul_f32 v[110:111], v[244:245], v[110:111] op_sel:[1,0]
	v_pk_mul_f32 v[104:105], v[244:245], v[104:105] op_sel:[1,0]
	v_pk_mul_f32 v[106:107], v[244:245], v[106:107] op_sel:[1,0]
	v_pk_fma_f32 v[108:109], v[198:199], v[108:109], v[232:233]
	v_pk_fma_f32 v[110:111], v[200:201], v[110:111], v[234:235]
	v_pk_fma_f32 v[104:105], v[202:203], v[104:105], v[236:237]
	v_pk_fma_f32 v[106:107], v[204:205], v[106:107], v[238:239]
	v_pk_fma_f32 v[84:85], v[108:109], s[0:1], v[84:85] op_sel_hi:[1,0,1]
	v_pk_fma_f32 v[86:87], v[110:111], s[0:1], v[86:87] op_sel_hi:[1,0,1]
	v_pk_fma_f32 v[80:81], v[104:105], s[0:1], v[80:81] op_sel_hi:[1,0,1]
	v_pk_fma_f32 v[82:83], v[106:107], s[0:1], v[82:83] op_sel_hi:[1,0,1]
	global_store_dwordx4 v128, v[84:87], s[44:45] offset:512
	global_store_dwordx4 v128, v[80:83], s[44:45] offset:528
	s_add_u32 s34, s34, s23
	s_addc_u32 s35, s35, 0
	global_load_dwordx4 v[84:87], v128, s[34:35]
	global_load_dwordx4 v[80:83], v128, s[34:35] offset:16
	global_load_dwordx2 v[210:211], v129, s[50:51] offset:1024
	s_waitcnt vmcnt(9)
	v_sub_f32_e32 v100, v100, v136
	v_sub_f32_e32 v101, v101, v136
	v_sub_f32_e32 v102, v102, v136
	v_sub_f32_e32 v103, v103, v136
	v_sub_f32_e32 v96, v96, v136
	v_sub_f32_e32 v97, v97, v136
	v_sub_f32_e32 v98, v98, v136
	v_sub_f32_e32 v99, v99, v136
	v_pk_mul_f32 v[100:101], v[136:137], v[100:101] op_sel:[1,0]
	v_pk_mul_f32 v[102:103], v[136:137], v[102:103] op_sel:[1,0]
	v_pk_mul_f32 v[96:97], v[136:137], v[96:97] op_sel:[1,0]
	v_pk_mul_f32 v[98:99], v[136:137], v[98:99] op_sel:[1,0]
	v_pk_fma_f32 v[100:101], v[190:191], v[100:101], v[224:225]
	v_pk_fma_f32 v[102:103], v[192:193], v[102:103], v[226:227]
	v_pk_fma_f32 v[96:97], v[194:195], v[96:97], v[228:229]
	v_pk_fma_f32 v[98:99], v[196:197], v[98:99], v[230:231]
	v_pk_fma_f32 v[76:77], v[100:101], s[0:1], v[76:77] op_sel_hi:[1,0,1]
	v_pk_fma_f32 v[78:79], v[102:103], s[0:1], v[78:79] op_sel_hi:[1,0,1]
	v_pk_fma_f32 v[72:73], v[96:97], s[0:1], v[72:73] op_sel_hi:[1,0,1]
	v_pk_fma_f32 v[74:75], v[98:99], s[0:1], v[74:75] op_sel_hi:[1,0,1]
	s_add_u32 s44, s44, s20
	s_addc_u32 s45, s45, 0
	global_store_dwordx4 v128, v[76:79], s[44:45]
	global_store_dwordx4 v128, v[72:75], s[44:45] offset:16
	global_load_dwordx4 v[76:79], v128, s[34:35] offset:512
	global_load_dwordx4 v[72:75], v128, s[34:35] offset:528
	s_waitcnt vmcnt(9)
	v_sub_f32_e32 v92, v92, v136
	v_sub_f32_e32 v93, v93, v136
	v_sub_f32_e32 v94, v94, v136
	v_sub_f32_e32 v95, v95, v136
	v_sub_f32_e32 v88, v88, v136
	v_sub_f32_e32 v89, v89, v136
	v_sub_f32_e32 v90, v90, v136
	v_sub_f32_e32 v91, v91, v136
	v_pk_mul_f32 v[92:93], v[136:137], v[92:93] op_sel:[1,0]
	v_pk_mul_f32 v[94:95], v[136:137], v[94:95] op_sel:[1,0]
	v_pk_mul_f32 v[88:89], v[136:137], v[88:89] op_sel:[1,0]
	v_pk_mul_f32 v[90:91], v[136:137], v[90:91] op_sel:[1,0]
	v_pk_fma_f32 v[92:93], v[198:199], v[92:93], v[232:233]
	v_pk_fma_f32 v[94:95], v[200:201], v[94:95], v[234:235]
	v_pk_fma_f32 v[88:89], v[202:203], v[88:89], v[236:237]
	v_pk_fma_f32 v[90:91], v[204:205], v[90:91], v[238:239]
	v_pk_fma_f32 v[68:69], v[92:93], s[0:1], v[68:69] op_sel_hi:[1,0,1]
	v_pk_fma_f32 v[70:71], v[94:95], s[0:1], v[70:71] op_sel_hi:[1,0,1]
	v_pk_fma_f32 v[64:65], v[88:89], s[0:1], v[64:65] op_sel_hi:[1,0,1]
	v_pk_fma_f32 v[66:67], v[90:91], s[0:1], v[66:67] op_sel_hi:[1,0,1]
	global_store_dwordx4 v128, v[68:71], s[44:45] offset:512
	global_store_dwordx4 v128, v[64:67], s[44:45] offset:528
	s_add_u32 s34, s34, s20
	s_addc_u32 s35, s35, 0
	global_load_dwordx4 v[68:71], v128, s[34:35]
	global_load_dwordx4 v[64:67], v128, s[34:35] offset:16
	global_load_dwordx2 v[244:245], v129, s[50:51] offset:1152
	s_waitcnt vmcnt(9)
	v_sub_f32_e32 v84, v84, v210
	v_sub_f32_e32 v85, v85, v210
	v_sub_f32_e32 v86, v86, v210
	v_sub_f32_e32 v87, v87, v210
	v_sub_f32_e32 v80, v80, v210
	v_sub_f32_e32 v81, v81, v210
	v_sub_f32_e32 v82, v82, v210
	v_sub_f32_e32 v83, v83, v210
	v_pk_mul_f32 v[84:85], v[210:211], v[84:85] op_sel:[1,0]
	v_pk_mul_f32 v[86:87], v[210:211], v[86:87] op_sel:[1,0]
	v_pk_mul_f32 v[80:81], v[210:211], v[80:81] op_sel:[1,0]
	v_pk_mul_f32 v[82:83], v[210:211], v[82:83] op_sel:[1,0]
	v_pk_fma_f32 v[84:85], v[190:191], v[84:85], v[224:225]
	v_pk_fma_f32 v[86:87], v[192:193], v[86:87], v[226:227]
	v_pk_fma_f32 v[80:81], v[194:195], v[80:81], v[228:229]
	v_pk_fma_f32 v[82:83], v[196:197], v[82:83], v[230:231]
	v_pk_fma_f32 v[60:61], v[84:85], s[0:1], v[60:61] op_sel_hi:[1,0,1]
	v_pk_fma_f32 v[62:63], v[86:87], s[0:1], v[62:63] op_sel_hi:[1,0,1]
	v_pk_fma_f32 v[56:57], v[80:81], s[0:1], v[56:57] op_sel_hi:[1,0,1]
	v_pk_fma_f32 v[58:59], v[82:83], s[0:1], v[58:59] op_sel_hi:[1,0,1]
	s_add_u32 s44, s44, s23
	s_addc_u32 s45, s45, 0
	global_store_dwordx4 v128, v[60:63], s[44:45]
	global_store_dwordx4 v128, v[56:59], s[44:45] offset:16
	global_load_dwordx4 v[60:63], v128, s[34:35] offset:512
	global_load_dwordx4 v[56:59], v128, s[34:35] offset:528
	s_waitcnt vmcnt(9)
; #define EPI_END } asm volatile("" ::: "memory"); }
;     __device__ __forceinline__ void operator()(const f32x4 (&acc)[2][2][4][2], const pg8::Unit& u, int wr, int wc, int fr, int fq) const {
;     ...
;             EPI_BEGIN { const size_t off = (size_t)row * ldc + col; f32x4 r0 = *(const f32x4*)(res + off), r1 = *(const f32x4*)(res + off + 4);
;                 if (p0) { const f32x2 ms = *(const f32x2*)(f0 + 2 * (size_t)row); const f32x4 g0 = *(const f32x4*)(p0 + col), g1 = *(const f32x4*)(p0 + col + 4), b0 = *(const f32x4*)(p1 + col), b1 = *(const f32x4*)(p1 + col + 4);
;                     r0 = (r0 - ms[0]) * ms[1] * g0 + b0; r1 = (r1 - ms[0]) * ms[1] * g1 + b1; }
;                 if (bias) { v0 += *(const f32x4*)(bias + col); v1 += *(const f32x4*)(bias + col + 4); }
;                 *(f32x4*)(outf + off) = r0 * ALPHA + v0; *(f32x4*)(outf + off + 4) = r1 * ALPHA + v1; } EPI_END
	v_sub_f32_e32 v76, v76, v210
	v_sub_f32_e32 v77, v77, v210
	v_sub_f32_e32 v78, v78, v210
	v_sub_f32_e32 v79, v79, v210
	v_sub_f32_e32 v72, v72, v210
	v_sub_f32_e32 v73, v73, v210
	v_sub_f32_e32 v74, v74, v210
	v_sub_f32_e32 v75, v75, v210
	v_pk_mul_f32 v[76:77], v[210:211], v[76:77] op_sel:[1,0]
	v_pk_mul_f32 v[78:79], v[210:211], v[78:79] op_sel:[1,0]
	v_pk_mul_f32 v[72:73], v[210:211], v[72:73] op_sel:[1,0]
	v_pk_mul_f32 v[74:75], v[210:211], v[74:75] op_sel:[1,0]
	v_pk_fma_f32 v[76:77], v[198:199], v[76:77], v[232:233]
	v_pk_fma_f32 v[78:79], v[200:201], v[78:79], v[234:235]
	v_pk_fma_f32 v[72:73], v[202:203], v[72:73], v[236:237]
	v_pk_fma_f32 v[74:75], v[204:205], v[74:75], v[238:239]
	v_pk_fma_f32 v[52:53], v[76:77], s[0:1], v[52:53] op_sel_hi:[1,0,1]
	v_pk_fma_f32 v[54:55], v[78:79], s[0:1], v[54:55] op_sel_hi:[1,0,1]
	v_pk_fma_f32 v[48:49], v[72:73], s[0:1], v[48:49] op_sel_hi:[1,0,1]
	v_pk_fma_f32 v[50:51], v[74:75], s[0:1], v[50:51] op_sel_hi:[1,0,1]
	global_store_dwordx4 v128, v[52:55], s[44:45] offset:512
	global_store_dwordx4 v128, v[48:51], s[44:45] offset:528
	s_add_u32 s34, s34, s20
	s_addc_u32 s35, s35, 0
	global_load_dwordx4 v[52:55], v128, s[34:35]
	global_load_dwordx4 v[48:51], v128, s[34:35] offset:16
	global_load_dwordx2 v[136:137], v129, s[50:51] offset:1280
	s_waitcnt vmcnt(9)
	v_sub_f32_e32 v68, v68, v244
	v_sub_f32_e32 v69, v69, v244
	v_sub_f32_e32 v70, v70, v244
	v_sub_f32_e32 v71, v71, v244
	v_sub_f32_e32 v64, v64, v244
	v_sub_f32_e32 v65, v65, v244
	v_sub_f32_e32 v66, v66, v244
	v_sub_f32_e32 v67, v67, v244
	v_pk_mul_f32 v[68:69], v[244:245], v[68:69] op_sel:[1,0]
	v_pk_mul_f32 v[70:71], v[244:245], v[70:71] op_sel:[1,0]
	v_pk_mul_f32 v[64:65], v[244:245], v[64:65] op_sel:[1,0]
	v_pk_mul_f32 v[66:67], v[244:245], v[66:67] op_sel:[1,0]
	v_pk_fma_f32 v[68:69], v[190:191], v[68:69], v[224:225]
	v_pk_fma_f32 v[70:71], v[192:193], v[70:71], v[226:227]
	v_pk_fma_f32 v[64:65], v[194:195], v[64:65], v[228:229]
	v_pk_fma_f32 v[66:67], v[196:197], v[66:67], v[230:231]
	v_pk_fma_f32 v[44:45], v[68:69], s[0:1], v[44:45] op_sel_hi:[1,0,1]
	v_pk_fma_f32 v[46:47], v[70:71], s[0:1], v[46:47] op_sel_hi:[1,0,1]
	v_pk_fma_f32 v[40:41], v[64:65], s[0:1], v[40:41] op_sel_hi:[1,0,1]
	v_pk_fma_f32 v[42:43], v[66:67], s[0:1], v[42:43] op_sel_hi:[1,0,1]
	s_add_u32 s44, s44, s20
	s_addc_u32 s45, s45, 0
	global_store_dwordx4 v128, v[44:47], s[44:45]
	global_store_dwordx4 v128, v[40:43], s[44:45] offset:16
	global_load_dwordx4 v[44:47], v128, s[34:35] offset:512
	global_load_dwordx4 v[40:43], v128, s[34:35] offset:528
	s_waitcnt vmcnt(9)
	v_sub_f32_e32 v60, v60, v244
	v_sub_f32_e32 v61, v61, v244
	v_sub_f32_e32 v62, v62, v244
	v_sub_f32_e32 v63, v63, v244
	v_sub_f32_e32 v56, v56, v244
	v_sub_f32_e32 v57, v57, v244
	v_sub_f32_e32 v58, v58, v244
	v_sub_f32_e32 v59, v59, v244
	v_pk_mul_f32 v[60:61], v[244:245], v[60:61] op_sel:[1,0]
	v_pk_mul_f32 v[62:63], v[244:245], v[62:63] op_sel:[1,0]
	v_pk_mul_f32 v[56:57], v[244:245], v[56:57] op_sel:[1,0]
	v_pk_mul_f32 v[58:59], v[244:245], v[58:59] op_sel:[1,0]
	v_pk_fma_f32 v[60:61], v[198:199], v[60:61], v[232:233]
	v_pk_fma_f32 v[62:63], v[200:201], v[62:63], v[234:235]
	v_pk_fma_f32 v[56:57], v[202:203], v[56:57], v[236:237]
	v_pk_fma_f32 v[58:59], v[204:205], v[58:59], v[238:239]
	v_pk_fma_f32 v[36:37], v[60:61], s[0:1], v[36:37] op_sel_hi:[1,0,1]
	v_pk_fma_f32 v[38:39], v[62:63], s[0:1], v[38:39] op_sel_hi:[1,0,1]
	v_pk_fma_f32 v[32:33], v[56:57], s[0:1], v[32:33] op_sel_hi:[1,0,1]
	v_pk_fma_f32 v[34:35], v[58:59], s[0:1], v[34:35] op_sel_hi:[1,0,1]
	global_store_dwordx4 v128, v[36:39], s[44:45] offset:512
	global_store_dwordx4 v128, v[32:35], s[44:45] offset:528
	s_add_u32 s34, s34, s20
	s_addc_u32 s35, s35, 0
	global_load_dwordx4 v[36:39], v128, s[34:35]
	global_load_dwordx4 v[32:35], v128, s[34:35] offset:16
	global_load_dwordx2 v[210:211], v129, s[50:51] offset:1408
	s_waitcnt vmcnt(9)
	v_sub_f32_e32 v52, v52, v136
	v_sub_f32_e32 v53, v53, v136
	v_sub_f32_e32 v54, v54, v136
	v_sub_f32_e32 v55, v55, v136
	v_sub_f32_e32 v48, v48, v136
	v_sub_f32_e32 v49, v49, v136
	v_sub_f32_e32 v50, v50, v136
	v_sub_f32_e32 v51, v51, v136
	v_pk_mul_f32 v[52:53], v[136:137], v[52:53] op_sel:[1,0]
	v_pk_mul_f32 v[54:55], v[136:137], v[54:55] op_sel:[1,0]
	v_pk_mul_f32 v[48:49], v[136:137], v[48:49] op_sel:[1,0]
	v_pk_mul_f32 v[50:51], v[136:137], v[50:51] op_sel:[1,0]
	v_pk_fma_f32 v[52:53], v[190:191], v[52:53], v[224:225]
	v_pk_fma_f32 v[54:55], v[192:193], v[54:55], v[226:227]
	v_pk_fma_f32 v[48:49], v[194:195], v[48:49], v[228:229]
	v_pk_fma_f32 v[50:51], v[196:197], v[50:51], v[230:231]
	v_pk_fma_f32 v[28:29], v[52:53], s[0:1], v[28:29] op_sel_hi:[1,0,1]
	v_pk_fma_f32 v[30:31], v[54:55], s[0:1], v[30:31] op_sel_hi:[1,0,1]
	v_pk_fma_f32 v[24:25], v[48:49], s[0:1], v[24:25] op_sel_hi:[1,0,1]
	v_pk_fma_f32 v[26:27], v[50:51], s[0:1], v[26:27] op_sel_hi:[1,0,1]
	s_add_u32 s44, s44, s20
	s_addc_u32 s45, s45, 0
	global_store_dwordx4 v128, v[28:31], s[44:45]
	global_store_dwordx4 v128, v[24:27], s[44:45] offset:16
	global_load_dwordx4 v[28:31], v128, s[34:35] offset:512
	global_load_dwordx4 v[24:27], v128, s[34:35] offset:528
	s_waitcnt vmcnt(9)
; #define EPI_END } asm volatile("" ::: "memory"); }
;     __device__ __forceinline__ void operator()(const f32x4 (&acc)[2][2][4][2], const pg8::Unit& u, int wr, int wc, int fr, int fq) const {
;     ...
;             EPI_BEGIN { const size_t off = (size_t)row * ldc + col; f32x4 r0 = *(const f32x4*)(res + off), r1 = *(const f32x4*)(res + off + 4);
;                 if (p0) { const f32x2 ms = *(const f32x2*)(f0 + 2 * (size_t)row); const f32x4 g0 = *(const f32x4*)(p0 + col), g1 = *(const f32x4*)(p0 + col + 4), b0 = *(const f32x4*)(p1 + col), b1 = *(const f32x4*)(p1 + col + 4);
;                     r0 = (r0 - ms[0]) * ms[1] * g0 + b0; r1 = (r1 - ms[0]) * ms[1] * g1 + b1; }
;                 if (bias) { v0 += *(const f32x4*)(bias + col); v1 += *(const f32x4*)(bias + col + 4); }
;                 *(f32x4*)(outf + off) = r0 * ALPHA + v0; *(f32x4*)(outf + off + 4) = r1 * ALPHA + v1; } EPI_END
	v_sub_f32_e32 v44, v44, v136
	v_sub_f32_e32 v45, v45, v136
	v_sub_f32_e32 v46, v46, v136
	v_sub_f32_e32 v47, v47, v136
	v_sub_f32_e32 v40, v40, v136
	v_sub_f32_e32 v41, v41, v136
	v_sub_f32_e32 v42, v42, v136
	v_sub_f32_e32 v43, v43, v136
	v_pk_mul_f32 v[44:45], v[136:137], v[44:45] op_sel:[1,0]
	v_pk_mul_f32 v[46:47], v[136:137], v[46:47] op_sel:[1,0]
	v_pk_mul_f32 v[40:41], v[136:137], v[40:41] op_sel:[1,0]
	v_pk_mul_f32 v[42:43], v[136:137], v[42:43] op_sel:[1,0]
	v_pk_fma_f32 v[44:45], v[198:199], v[44:45], v[232:233]
	v_pk_fma_f32 v[46:47], v[200:201], v[46:47], v[234:235]
	v_pk_fma_f32 v[40:41], v[202:203], v[40:41], v[236:237]
	v_pk_fma_f32 v[42:43], v[204:205], v[42:43], v[238:239]
	v_pk_fma_f32 v[20:21], v[44:45], s[0:1], v[20:21] op_sel_hi:[1,0,1]
	v_pk_fma_f32 v[22:23], v[46:47], s[0:1], v[22:23] op_sel_hi:[1,0,1]
	v_pk_fma_f32 v[16:17], v[40:41], s[0:1], v[16:17] op_sel_hi:[1,0,1]
	v_pk_fma_f32 v[18:19], v[42:43], s[0:1], v[18:19] op_sel_hi:[1,0,1]
	global_store_dwordx4 v128, v[20:23], s[44:45] offset:512
	global_store_dwordx4 v128, v[16:19], s[44:45] offset:528
	s_waitcnt vmcnt(6)
	v_sub_f32_e32 v36, v36, v210
	v_sub_f32_e32 v37, v37, v210
	v_sub_f32_e32 v38, v38, v210
	v_sub_f32_e32 v39, v39, v210
	v_sub_f32_e32 v32, v32, v210
	v_sub_f32_e32 v33, v33, v210
	v_sub_f32_e32 v34, v34, v210
	v_sub_f32_e32 v35, v35, v210
	v_pk_mul_f32 v[36:37], v[210:211], v[36:37] op_sel:[1,0]
	v_pk_mul_f32 v[38:39], v[210:211], v[38:39] op_sel:[1,0]
	v_pk_mul_f32 v[32:33], v[210:211], v[32:33] op_sel:[1,0]
	v_pk_mul_f32 v[34:35], v[210:211], v[34:35] op_sel:[1,0]
	v_pk_fma_f32 v[36:37], v[190:191], v[36:37], v[224:225]
	v_pk_fma_f32 v[38:39], v[192:193], v[38:39], v[226:227]
	v_pk_fma_f32 v[32:33], v[194:195], v[32:33], v[228:229]
	v_pk_fma_f32 v[34:35], v[196:197], v[34:35], v[230:231]
	v_pk_fma_f32 v[12:13], v[36:37], s[0:1], v[12:13] op_sel_hi:[1,0,1]
	v_pk_fma_f32 v[14:15], v[38:39], s[0:1], v[14:15] op_sel_hi:[1,0,1]
	v_pk_fma_f32 v[8:9], v[32:33], s[0:1], v[8:9] op_sel_hi:[1,0,1]
	v_pk_fma_f32 v[10:11], v[34:35], s[0:1], v[10:11] op_sel_hi:[1,0,1]
	s_add_u32 s44, s44, s20
	s_addc_u32 s45, s45, 0
	global_store_dwordx4 v128, v[12:15], s[44:45]
	global_store_dwordx4 v128, v[8:11], s[44:45] offset:16
	s_waitcnt vmcnt(4)
	v_sub_f32_e32 v28, v28, v210
	v_sub_f32_e32 v29, v29, v210
	v_sub_f32_e32 v30, v30, v210
	v_sub_f32_e32 v31, v31, v210
	v_sub_f32_e32 v24, v24, v210
	v_sub_f32_e32 v25, v25, v210
	v_sub_f32_e32 v26, v26, v210
	v_sub_f32_e32 v27, v27, v210
	v_pk_mul_f32 v[28:29], v[210:211], v[28:29] op_sel:[1,0]
	v_pk_mul_f32 v[30:31], v[210:211], v[30:31] op_sel:[1,0]
	v_pk_mul_f32 v[24:25], v[210:211], v[24:25] op_sel:[1,0]
	v_pk_mul_f32 v[26:27], v[210:211], v[26:27] op_sel:[1,0]
	v_pk_fma_f32 v[28:29], v[198:199], v[28:29], v[232:233]
	v_pk_fma_f32 v[30:31], v[200:201], v[30:31], v[234:235]
	v_pk_fma_f32 v[24:25], v[202:203], v[24:25], v[236:237]
	v_pk_fma_f32 v[26:27], v[204:205], v[26:27], v[238:239]
	v_pk_fma_f32 v[4:5], v[28:29], s[0:1], v[4:5] op_sel_hi:[1,0,1]
	v_pk_fma_f32 v[6:7], v[30:31], s[0:1], v[6:7] op_sel_hi:[1,0,1]
	v_pk_fma_f32 v[0:1], v[24:25], s[0:1], v[0:1] op_sel_hi:[1,0,1]
	v_pk_fma_f32 v[2:3], v[26:27], s[0:1], v[2:3] op_sel_hi:[1,0,1]
	global_store_dwordx4 v128, v[4:7], s[44:45] offset:512
	global_store_dwordx4 v128, v[0:3], s[44:45] offset:528
	s_branch .LBB0_1237
.Lmy_res_noln:
	global_load_dwordx4 v[132:135], v128, s[34:35]
	global_load_dwordx4 v[156:159], v128, s[34:35] offset:16
	global_load_dwordx4 v[176:179], v128, s[34:35] offset:512
	global_load_dwordx4 v[206:209], v128, s[34:35] offset:528
	s_add_u32 s34, s34, s20
	s_addc_u32 s35, s35, 0
	global_load_dwordx4 v[240:243], v128, s[34:35]
	global_load_dwordx4 v[160:163], v128, s[34:35] offset:16
	s_waitcnt vmcnt(4)
	v_pk_fma_f32 v[124:125], v[132:133], s[0:1], v[124:125] op_sel_hi:[1,0,1]
	v_pk_fma_f32 v[126:127], v[134:135], s[0:1], v[126:127] op_sel_hi:[1,0,1]
	v_pk_fma_f32 v[120:121], v[156:157], s[0:1], v[120:121] op_sel_hi:[1,0,1]
	v_pk_fma_f32 v[122:123], v[158:159], s[0:1], v[122:123] op_sel_hi:[1,0,1]
	global_store_dwordx4 v128, v[124:127], s[44:45]
	global_store_dwordx4 v128, v[120:123], s[44:45] offset:16
	global_load_dwordx4 v[124:127], v128, s[34:35] offset:512
	global_load_dwordx4 v[120:123], v128, s[34:35] offset:528
	s_waitcnt vmcnt(6)
	v_pk_fma_f32 v[116:117], v[176:177], s[0:1], v[116:117] op_sel_hi:[1,0,1]
	v_pk_fma_f32 v[118:119], v[178:179], s[0:1], v[118:119] op_sel_hi:[1,0,1]
	v_pk_fma_f32 v[112:113], v[206:207], s[0:1], v[112:113] op_sel_hi:[1,0,1]
	v_pk_fma_f32 v[114:115], v[208:209], s[0:1], v[114:115] op_sel_hi:[1,0,1]
	global_store_dwordx4 v128, v[116:119], s[44:45] offset:512
	global_store_dwordx4 v128, v[112:115], s[44:45] offset:528
	s_add_u32 s34, s34, s20
	s_addc_u32 s35, s35, 0
	global_load_dwordx4 v[116:119], v128, s[34:35]
	global_load_dwordx4 v[112:115], v128, s[34:35] offset:16
	s_waitcnt vmcnt(8)
	v_pk_fma_f32 v[108:109], v[240:241], s[0:1], v[108:109] op_sel_hi:[1,0,1]
	v_pk_fma_f32 v[110:111], v[242:243], s[0:1], v[110:111] op_sel_hi:[1,0,1]
	v_pk_fma_f32 v[104:105], v[160:161], s[0:1], v[104:105] op_sel_hi:[1,0,1]
	v_pk_fma_f32 v[106:107], v[162:163], s[0:1], v[106:107] op_sel_hi:[1,0,1]
	s_add_u32 s44, s44, s20
	s_addc_u32 s45, s45, 0
	global_store_dwordx4 v128, v[108:111], s[44:45]
	global_store_dwordx4 v128, v[104:107], s[44:45] offset:16
	global_load_dwordx4 v[108:111], v128, s[34:35] offset:512
	global_load_dwordx4 v[104:107], v128, s[34:35] offset:528
	s_waitcnt vmcnt(8)
; #define EPI_END } asm volatile("" ::: "memory"); }
;     __device__ __forceinline__ void operator()(const f32x4 (&acc)[2][2][4][2], const pg8::Unit& u, int wr, int wc, int fr, int fq) const {
;     ...
;             EPI_BEGIN { const size_t off = (size_t)row * ldc + col; f32x4 r0 = *(const f32x4*)(res + off), r1 = *(const f32x4*)(res + off + 4);
;                 if (p0) { const f32x2 ms = *(const f32x2*)(f0 + 2 * (size_t)row); const f32x4 g0 = *(const f32x4*)(p0 + col), g1 = *(const f32x4*)(p0 + col + 4), b0 = *(const f32x4*)(p1 + col), b1 = *(const f32x4*)(p1 + col + 4);
;                     r0 = (r0 - ms[0]) * ms[1] * g0 + b0; r1 = (r1 - ms[0]) * ms[1] * g1 + b1; }
;                 if (bias) { v0 += *(const f32x4*)(bias + col); v1 += *(const f32x4*)(bias + col + 4); }
;                 *(f32x4*)(outf + off) = r0 * ALPHA + v0; *(f32x4*)(outf + off + 4) = r1 * ALPHA + v1; } EPI_END
	v_pk_fma_f32 v[100:101], v[124:125], s[0:1], v[100:101] op_sel_hi:[1,0,1]
	v_pk_fma_f32 v[102:103], v[126:127], s[0:1], v[102:103] op_sel_hi:[1,0,1]
	v_pk_fma_f32 v[96:97], v[120:121], s[0:1], v[96:97] op_sel_hi:[1,0,1]
	v_pk_fma_f32 v[98:99], v[122:123], s[0:1], v[98:99] op_sel_hi:[1,0,1]
	global_store_dwordx4 v128, v[100:103], s[44:45] offset:512
	global_store_dwordx4 v128, v[96:99], s[44:45] offset:528
	s_add_u32 s34, s34, s20
	s_addc_u32 s35, s35, 0
	global_load_dwordx4 v[100:103], v128, s[34:35]
	global_load_dwordx4 v[96:99], v128, s[34:35] offset:16
	s_waitcnt vmcnt(8)
	v_pk_fma_f32 v[92:93], v[116:117], s[0:1], v[92:93] op_sel_hi:[1,0,1]
	v_pk_fma_f32 v[94:95], v[118:119], s[0:1], v[94:95] op_sel_hi:[1,0,1]
	v_pk_fma_f32 v[88:89], v[112:113], s[0:1], v[88:89] op_sel_hi:[1,0,1]
	v_pk_fma_f32 v[90:91], v[114:115], s[0:1], v[90:91] op_sel_hi:[1,0,1]
	s_add_u32 s44, s44, s20
	s_addc_u32 s45, s45, 0
	global_store_dwordx4 v128, v[92:95], s[44:45]
	global_store_dwordx4 v128, v[88:91], s[44:45] offset:16
	global_load_dwordx4 v[92:95], v128, s[34:35] offset:512
	global_load_dwordx4 v[88:91], v128, s[34:35] offset:528
	s_waitcnt vmcnt(8)
	v_pk_fma_f32 v[84:85], v[108:109], s[0:1], v[84:85] op_sel_hi:[1,0,1]
	v_pk_fma_f32 v[86:87], v[110:111], s[0:1], v[86:87] op_sel_hi:[1,0,1]
	v_pk_fma_f32 v[80:81], v[104:105], s[0:1], v[80:81] op_sel_hi:[1,0,1]
	v_pk_fma_f32 v[82:83], v[106:107], s[0:1], v[82:83] op_sel_hi:[1,0,1]
	global_store_dwordx4 v128, v[84:87], s[44:45] offset:512
	global_store_dwordx4 v128, v[80:83], s[44:45] offset:528
	s_add_u32 s34, s34, s23
	s_addc_u32 s35, s35, 0
	global_load_dwordx4 v[84:87], v128, s[34:35]
	global_load_dwordx4 v[80:83], v128, s[34:35] offset:16
	s_waitcnt vmcnt(8)
	v_pk_fma_f32 v[76:77], v[100:101], s[0:1], v[76:77] op_sel_hi:[1,0,1]
	v_pk_fma_f32 v[78:79], v[102:103], s[0:1], v[78:79] op_sel_hi:[1,0,1]
	v_pk_fma_f32 v[72:73], v[96:97], s[0:1], v[72:73] op_sel_hi:[1,0,1]
	v_pk_fma_f32 v[74:75], v[98:99], s[0:1], v[74:75] op_sel_hi:[1,0,1]
	s_add_u32 s44, s44, s20
	s_addc_u32 s45, s45, 0
	global_store_dwordx4 v128, v[76:79], s[44:45]
	global_store_dwordx4 v128, v[72:75], s[44:45] offset:16
	global_load_dwordx4 v[76:79], v128, s[34:35] offset:512
	global_load_dwordx4 v[72:75], v128, s[34:35] offset:528
	s_waitcnt vmcnt(8)
	v_pk_fma_f32 v[68:69], v[92:93], s[0:1], v[68:69] op_sel_hi:[1,0,1]
	v_pk_fma_f32 v[70:71], v[94:95], s[0:1], v[70:71] op_sel_hi:[1,0,1]
	v_pk_fma_f32 v[64:65], v[88:89], s[0:1], v[64:65] op_sel_hi:[1,0,1]
	v_pk_fma_f32 v[66:67], v[90:91], s[0:1], v[66:67] op_sel_hi:[1,0,1]
	global_store_dwordx4 v128, v[68:71], s[44:45] offset:512
	global_store_dwordx4 v128, v[64:67], s[44:45] offset:528
	s_add_u32 s34, s34, s20
	s_addc_u32 s35, s35, 0
	global_load_dwordx4 v[68:71], v128, s[34:35]
	global_load_dwordx4 v[64:67], v128, s[34:35] offset:16
	s_waitcnt vmcnt(8)
	v_pk_fma_f32 v[60:61], v[84:85], s[0:1], v[60:61] op_sel_hi:[1,0,1]
	v_pk_fma_f32 v[62:63], v[86:87], s[0:1], v[62:63] op_sel_hi:[1,0,1]
	v_pk_fma_f32 v[56:57], v[80:81], s[0:1], v[56:57] op_sel_hi:[1,0,1]
	v_pk_fma_f32 v[58:59], v[82:83], s[0:1], v[58:59] op_sel_hi:[1,0,1]
	s_add_u32 s44, s44, s23
	s_addc_u32 s45, s45, 0
	global_store_dwordx4 v128, v[60:63], s[44:45]
	global_store_dwordx4 v128, v[56:59], s[44:45] offset:16
	global_load_dwordx4 v[60:63], v128, s[34:35] offset:512
	global_load_dwordx4 v[56:59], v128, s[34:35] offset:528
	s_waitcnt vmcnt(8)
	v_pk_fma_f32 v[52:53], v[76:77], s[0:1], v[52:53] op_sel_hi:[1,0,1]
	v_pk_fma_f32 v[54:55], v[78:79], s[0:1], v[54:55] op_sel_hi:[1,0,1]
	v_pk_fma_f32 v[48:49], v[72:73], s[0:1], v[48:49] op_sel_hi:[1,0,1]
	v_pk_fma_f32 v[50:51], v[74:75], s[0:1], v[50:51] op_sel_hi:[1,0,1]
	global_store_dwordx4 v128, v[52:55], s[44:45] offset:512
	global_store_dwordx4 v128, v[48:51], s[44:45] offset:528
	s_add_u32 s34, s34, s20
	s_addc_u32 s35, s35, 0
	global_load_dwordx4 v[52:55], v128, s[34:35]
	global_load_dwordx4 v[48:51], v128, s[34:35] offset:16
	s_waitcnt vmcnt(8)
	v_pk_fma_f32 v[44:45], v[68:69], s[0:1], v[44:45] op_sel_hi:[1,0,1]
	v_pk_fma_f32 v[46:47], v[70:71], s[0:1], v[46:47] op_sel_hi:[1,0,1]
	v_pk_fma_f32 v[40:41], v[64:65], s[0:1], v[40:41] op_sel_hi:[1,0,1]
	v_pk_fma_f32 v[42:43], v[66:67], s[0:1], v[42:43] op_sel_hi:[1,0,1]
	s_add_u32 s44, s44, s20
	s_addc_u32 s45, s45, 0
	global_store_dwordx4 v128, v[44:47], s[44:45]
	global_store_dwordx4 v128, v[40:43], s[44:45] offset:16
	global_load_dwordx4 v[44:47], v128, s[34:35] offset:512
	global_load_dwordx4 v[40:43], v128, s[34:35] offset:528
	s_waitcnt vmcnt(8)
	v_pk_fma_f32 v[36:37], v[60:61], s[0:1], v[36:37] op_sel_hi:[1,0,1]
	v_pk_fma_f32 v[38:39], v[62:63], s[0:1], v[38:39] op_sel_hi:[1,0,1]
	v_pk_fma_f32 v[32:33], v[56:57], s[0:1], v[32:33] op_sel_hi:[1,0,1]
	v_pk_fma_f32 v[34:35], v[58:59], s[0:1], v[34:35] op_sel_hi:[1,0,1]
	global_store_dwordx4 v128, v[36:39], s[44:45] offset:512
	global_store_dwordx4 v128, v[32:35], s[44:45] offset:528
	s_add_u32 s34, s34, s20
	s_addc_u32 s35, s35, 0
	global_load_dwordx4 v[36:39], v128, s[34:35]
	global_load_dwordx4 v[32:35], v128, s[34:35] offset:16
	s_waitcnt vmcnt(8)
	v_pk_fma_f32 v[28:29], v[52:53], s[0:1], v[28:29] op_sel_hi:[1,0,1]
	v_pk_fma_f32 v[30:31], v[54:55], s[0:1], v[30:31] op_sel_hi:[1,0,1]
	v_pk_fma_f32 v[24:25], v[48:49], s[0:1], v[24:25] op_sel_hi:[1,0,1]
	v_pk_fma_f32 v[26:27], v[50:51], s[0:1], v[26:27] op_sel_hi:[1,0,1]
	s_add_u32 s44, s44, s20
	s_addc_u32 s45, s45, 0
	global_store_dwordx4 v128, v[28:31], s[44:45]
	global_store_dwordx4 v128, v[24:27], s[44:45] offset:16
	global_load_dwordx4 v[28:31], v128, s[34:35] offset:512
	global_load_dwordx4 v[24:27], v128, s[34:35] offset:528
	s_waitcnt vmcnt(8)
	v_pk_fma_f32 v[20:21], v[44:45], s[0:1], v[20:21] op_sel_hi:[1,0,1]
	v_pk_fma_f32 v[22:23], v[46:47], s[0:1], v[22:23] op_sel_hi:[1,0,1]
	v_pk_fma_f32 v[16:17], v[40:41], s[0:1], v[16:17] op_sel_hi:[1,0,1]
	v_pk_fma_f32 v[18:19], v[42:43], s[0:1], v[18:19] op_sel_hi:[1,0,1]
	global_store_dwordx4 v128, v[20:23], s[44:45] offset:512
	global_store_dwordx4 v128, v[16:19], s[44:45] offset:528
	s_waitcnt vmcnt(6)
	v_pk_fma_f32 v[12:13], v[36:37], s[0:1], v[12:13] op_sel_hi:[1,0,1]
	v_pk_fma_f32 v[14:15], v[38:39], s[0:1], v[14:15] op_sel_hi:[1,0,1]
	v_pk_fma_f32 v[8:9], v[32:33], s[0:1], v[8:9] op_sel_hi:[1,0,1]
	v_pk_fma_f32 v[10:11], v[34:35], s[0:1], v[10:11] op_sel_hi:[1,0,1]
	s_add_u32 s44, s44, s20
	s_addc_u32 s45, s45, 0
	global_store_dwordx4 v128, v[12:15], s[44:45]
	global_store_dwordx4 v128, v[8:11], s[44:45] offset:16
	s_waitcnt vmcnt(4)
	v_pk_fma_f32 v[4:5], v[28:29], s[0:1], v[4:5] op_sel_hi:[1,0,1]
	v_pk_fma_f32 v[6:7], v[30:31], s[0:1], v[6:7] op_sel_hi:[1,0,1]
	v_pk_fma_f32 v[0:1], v[24:25], s[0:1], v[0:1] op_sel_hi:[1,0,1]
	v_pk_fma_f32 v[2:3], v[26:27], s[0:1], v[2:3] op_sel_hi:[1,0,1]
	global_store_dwordx4 v128, v[4:7], s[44:45] offset:512
	global_store_dwordx4 v128, v[0:3], s[44:45] offset:528
